# v104 + second queue in natural order: DSA rounds first, gating/conv items last (fill for workgroups that finish FoX early)
# baseline (speedup 1.0000x reference)
;     ...
;     auto fetch = [&]() -> int {
;         auto q1 = [&](int i) -> int { return i < N_A + N_C ? N_D + N_B + i : N_D + (i - (N_A + N_C)); };
;         if (pref == 0) { int i = (int)atomicAdd(ctr, 1u); if (i < N_D) return i; i = (int)atomicAdd(ctr + 32, 1u); return i < N_ALL - N_D ? q1(i) : N_ALL; }
;         int i = (int)atomicAdd(ctr + 32, 1u); if (i < N_ALL - N_D) return q1(i); i = (int)atomicAdd(ctr, 1u); return i < N_D ? i : N_ALL; };
.LBB0_120:
	s_andn2_saveexec_b64 s[20:21], s[20:21]
	s_movk_i32 s22, 0x100
	v_add_u32_e32 v2, 0x100, v0
	v_cmp_gt_i32_e32 vcc, s22, v0
	s_nop 1
	v_mov_b32_e32 v180, v2
	s_or_b64 exec, exec, s[20:21]
	s_branch .LBB0_131

;     ...
;     auto fetch = [&]() -> int {
;         auto q1 = [&](int i) -> int { return i < N_A + N_C ? N_D + N_B + i : N_D + (i - (N_A + N_C)); };
;         if (pref == 0) { int i = (int)atomicAdd(ctr, 1u); if (i < N_D) return i; i = (int)atomicAdd(ctr + 32, 1u); return i < N_ALL - N_D ? q1(i) : N_ALL; }
;         int i = (int)atomicAdd(ctr + 32, 1u); if (i < N_ALL - N_D) return q1(i); i = (int)atomicAdd(ctr, 1u); return i < N_D ? i : N_ALL; };
.LBB0_129:
	s_or_b64 exec, exec, s[22:23]
	s_waitcnt vmcnt(0)
	v_readfirstlane_b32 s22, v2
	s_nop 1
	v_add_u32_e32 v0, s22, v0
	s_movk_i32 s22, 0x100
	v_add_u32_e32 v2, 0x100, v0
	v_cmp_gt_i32_e32 vcc, s22, v0
	s_movk_i32 s22, 0x900
	s_nop 0
	s_nop 0
	v_cmp_gt_i32_e32 vcc, s22, v0
	s_nop 1
	v_cndmask_b32_e32 v180, v204, v2, vcc

;     ...
;     auto fetch = [&]() -> int {
;         auto q1 = [&](int i) -> int { return i < N_A + N_C ? N_D + N_B + i : N_D + (i - (N_A + N_C)); };
;         if (pref == 0) { int i = (int)atomicAdd(ctr, 1u); if (i < N_D) return i; i = (int)atomicAdd(ctr + 32, 1u); return i < N_ALL - N_D ? q1(i) : N_ALL; }
;         int i = (int)atomicAdd(ctr + 32, 1u); if (i < N_ALL - N_D) return q1(i); i = (int)atomicAdd(ctr, 1u); return i < N_D ? i : N_ALL; };
.LBB0_144:
	s_andn2_saveexec_b64 s[20:21], s[20:21]
	s_movk_i32 s22, 0x100
	v_add_u32_e32 v2, 0x100, v0
	v_cmp_gt_i32_e32 vcc, s22, v0
	s_nop 1
	v_mov_b32_e32 v180, v2
	s_or_b64 exec, exec, s[20:21]
